# speedup vs baseline: 1.0329x; 1.0219x over previous
; DI int get_tid_(int wv) { int z = 0; asm volatile("" : "+v"(z)); asm volatile("" : "+s"(wv)); const int lane = __builtin_amdgcn_mbcnt_hi(~0u, __builtin_amdgcn_mbcnt_lo(~0u, z)); return (wv << 6) | lane; }
; DI ARef mkref(const PP& p, int L, bool dummy = false) {
;     const int qb = 63 - (L >> 3), hh = L & 7;
;     ARef r;
;     r.Q = p.proj + (size_t)(qb * QB) * LDP + C_FQ + hh * 128; r.O = p.proj + (size_t)(qb * QB) * LDP + C_FQ + hh * 128;
; DI void phase(const PP& p, unsigned* ctr, int base, int total, char* lds, const unsigned* nrm, bool dummy = false) {
;     const int tid = get_tid_(p.wv);
;     volatile int* slot = (volatile int*)(lds + OFF_SLOT);
;     __syncthreads();
;     if (tid == 0) *slot = (int)atomicAdd(ctr, 1u);
;     __syncthreads();
;     int L = __builtin_amdgcn_readfirstlane(*slot);
;     __syncthreads();
;     if (L >= total) return;
;     ARef cur = mkref(p, base + L, dummy); Seam S;
.LBB0_505:
	s_or_b64 exec, exec, s[2:3]
	s_add_i32 s78, 0, 0x10a00
	s_mov_b64 s[2:3], src_shared_base
	s_cmp_lg_u32 s78, -1
	s_cselect_b32 s1, s78, 0
	s_cselect_b32 s2, s3, 0
	v_mov_b32_e32 v2, s1
	v_mov_b32_e32 v3, s2
	s_waitcnt lgkmcnt(0)
	s_barrier
	flat_load_dword v2, v[2:3] sc0 sc1
	s_waitcnt vmcnt(0) lgkmcnt(0)
	s_barrier
	v_readfirstlane_b32 s1, v2
	s_cmpk_gt_i32 s1, 0x2ff
	s_cbranch_scc1 .LBB0_717
	v_writelane_b32 v255, s0, 46
	s_cmpk_lt_u32 s1, 384
	s_cbranch_scc1 .Lfa_m1_a
	s_cmpk_lt_u32 s1, 640
	s_cbranch_scc1 .Lfa_m1_b
	s_sub_i32 s1, s1, 256
	s_mov_b32 s3, 2
	s_branch .Lfa_m1_md
.Lfa_m1_b:
	s_sub_i32 s2, s1, 384
	s_and_b32 s3, s2, 15
	s_lshr_b32 s2, s2, 4
	s_lshl_b32 s2, s2, 3
	s_addk_i32 s2, 128
	s_lshr_b32 s1, s3, 1
	s_add_i32 s1, s1, s2
	s_and_b32 s3, s3, 1
	s_branch .Lfa_m1_md
.Lfa_m1_a:
	s_mul_i32 s2, s1, 0xaaab
	s_lshr_b32 s2, s2, 20
	s_mul_i32 s3, s2, 24
	s_sub_i32 s3, s1, s3
	s_lshl_b32 s2, s2, 3
	s_cmp_lt_u32 s3, 16
	s_cbranch_scc0 .Lfa_m1_uns
	s_lshr_b32 s1, s3, 1
	s_add_i32 s1, s1, s2
	s_and_b32 s3, s3, 1
	s_branch .Lfa_m1_md

; #define MFMA32(a, b, c) __builtin_amdgcn_mfma_f32_32x32x16_bf16((a), (b), (c), 0, 0, 0)
; DI void finishSM(f32x16& p0, f32x16& p1, float alpha, float& l_reg, bf16x8& pa0, bf16x8& pa1, bf16x8& pa2, bf16x8& pa3) {
; #pragma unroll
;     for (int r = 0; r < 16; ++r) p1[r] = __builtin_amdgcn_exp2f(p1[r]);
;     float ps = 0;
; #pragma unroll
;     for (int r = 0; r < 16; ++r) ps += p0[r];
; #pragma unroll
;     for (int r = 0; r < 16; ++r) ps += p1[r];
;     { auto rr = __builtin_amdgcn_permlane32_swap(__float_as_uint(ps), __float_as_uint(ps), false, false);
;       ps = __uint_as_float(rr[0]) + __uint_as_float(rr[1]); }
;     l_reg = l_reg * alpha + ps;
;     ...
;     PK4(p0, 0, pa0); PK4(p0, 8, pa1); PK4(p1, 0, pa2); PK4(p1, 8, pa3);
;     ...
; }
; template <int KB>
; DI void qkt(f32x16& p0, f32x16& p1, const char* K_lds, int r32, int hi, const bf16x8* qr, const float* bb) {
; #pragma unroll
;     for (int g = 0; g < 4; ++g) {
;         const f32x4 b0 = *(const f32x4*)(bb + KB * 64 + 8 * g), b1 = *(const f32x4*)(bb + KB * 64 + 32 + 8 * g);
; #pragma unroll
;         for (int j = 0; j < 4; ++j) { p0[4 * g + j] = b0[j]; p1[4 * g + j] = b1[j]; }
;     }
;     const char* kb[4];
; #pragma unroll
;     for (int dd = 0; dd < 4; ++dd) kb[dd] = K_lds + KB * SHM_K + KSWZ(r32, (dd * 16 + hi * 8) * 2);
; #pragma unroll
;     for (int d0 = 0; d0 < 8; ++d0) { const char* a = kb[d0 & 3] + (d0 >> 2) * 128;
;         bf16x8 b0 = *reinterpret_cast<const bf16x8*>(a);
;         bf16x8 b1 = *reinterpret_cast<const bf16x8*>(a + 32 * 256);
;         p0 = MFMA32(b0, qr[d0], p0);
;         p1 = MFMA32(b1, qr[d0], p1); }
; }
.LBB0_536:
	s_or_b64 exec, exec, s[0:1]
	ds_read_b128 v[86:89], v235 offset:256
	ds_read_b128 v[90:93], v235 offset:288
	ds_read_b128 v[70:73], v235 offset:384
	ds_read_b128 v[74:77], v235 offset:416
	ds_read_b128 v[94:97], v235 offset:320
	ds_read_b128 v[78:81], v235 offset:448
	s_waitcnt vmcnt(0)
	ds_read_b128 v[98:101], v235 offset:352
	ds_read_b128 v[82:85], v235 offset:480
	ds_read_b128 v[66:69], v233 offset:49152
	ds_read_b128 v[102:105], v233 offset:57344
	v_exp_f32_e32 v106, v128
	v_exp_f32_e32 v107, v129
	v_exp_f32_e32 v108, v126
	s_waitcnt lgkmcnt(0)
	v_mfma_f32_32x32x16_bf16 v[86:101], v[66:69], v[158:161], v[86:101]
	v_exp_f32_e32 v109, v127
	v_exp_f32_e32 v110, v124
	v_exp_f32_e32 v111, v125
	v_exp_f32_e32 v112, v122
	v_exp_f32_e32 v113, v123
	v_exp_f32_e32 v120, v120
	v_exp_f32_e32 v121, v121
	v_mfma_f32_32x32x16_bf16 v[70:85], v[102:105], v[158:161], v[70:85]
	ds_read_b128 v[66:69], v234 offset:49152
	ds_read_b128 v[102:105], v234 offset:57344
	v_exp_f32_e32 v118, v118
	v_exp_f32_e32 v119, v119
	v_exp_f32_e32 v116, v116
	v_exp_f32_e32 v117, v117
	v_exp_f32_e32 v114, v114
	v_exp_f32_e32 v115, v115
	s_waitcnt lgkmcnt(1)
	v_mfma_f32_32x32x16_bf16 v[86:101], v[66:69], v[154:157], v[86:101]
	s_waitcnt lgkmcnt(0)
	v_mfma_f32_32x32x16_bf16 v[70:85], v[102:105], v[154:157], v[70:85]
	ds_read_b128 v[66:69], v232 offset:49152
	ds_read_b128 v[102:105], v232 offset:57344
	s_waitcnt lgkmcnt(1)
	v_mfma_f32_32x32x16_bf16 v[86:101], v[66:69], v[150:153], v[86:101]
	s_waitcnt lgkmcnt(0)
	v_mfma_f32_32x32x16_bf16 v[70:85], v[102:105], v[150:153], v[70:85]
	ds_read_b128 v[66:69], v231 offset:49152
	ds_read_b128 v[102:105], v231 offset:57344
	s_waitcnt lgkmcnt(1)
	v_mfma_f32_32x32x16_bf16 v[86:101], v[66:69], v[146:149], v[86:101]
	s_waitcnt lgkmcnt(0)
	v_mfma_f32_32x32x16_bf16 v[70:85], v[102:105], v[146:149], v[70:85]
	ds_read_b128 v[66:69], v233 offset:49280
	ds_read_b128 v[102:105], v233 offset:57472
	s_waitcnt lgkmcnt(1)
	v_mfma_f32_32x32x16_bf16 v[86:101], v[66:69], v[142:145], v[86:101]
	s_waitcnt lgkmcnt(0)
	v_mfma_f32_32x32x16_bf16 v[70:85], v[102:105], v[142:145], v[70:85]
	ds_read_b128 v[66:69], v234 offset:49280
	ds_read_b128 v[102:105], v234 offset:57472
	s_waitcnt lgkmcnt(1)
	v_mfma_f32_32x32x16_bf16 v[86:101], v[66:69], v[138:141], v[86:101]
	s_waitcnt lgkmcnt(0)
	v_mfma_f32_32x32x16_bf16 v[70:85], v[102:105], v[138:141], v[70:85]
	ds_read_b128 v[66:69], v232 offset:49280
	ds_read_b128 v[102:105], v232 offset:57472
	s_waitcnt lgkmcnt(1)
	v_mfma_f32_32x32x16_bf16 v[86:101], v[66:69], v[134:137], v[86:101]
	s_waitcnt lgkmcnt(0)
	v_mfma_f32_32x32x16_bf16 v[70:85], v[102:105], v[134:137], v[70:85]
	ds_read_b128 v[66:69], v231 offset:49280
	ds_read_b128 v[102:105], v231 offset:57472
	s_waitcnt lgkmcnt(1)
	v_mfma_f32_32x32x16_bf16 v[86:101], v[66:69], v[130:133], v[86:101]
	v_add_f32_e32 v66, 0, v176
	v_add_f32_e32 v66, v179, v66
	v_add_f32_e32 v66, v174, v66
	v_add_f32_e32 v66, v177, v66
	v_add_f32_e32 v66, v173, v66
	v_add_f32_e32 v66, v175, v66
	v_add_f32_e32 v66, v171, v66
	v_add_f32_e32 v66, v172, v66
	v_add_f32_e32 v66, v167, v66
	v_add_f32_e32 v66, v170, v66
	v_add_f32_e32 v66, v165, v66
	v_add_f32_e32 v66, v168, v66
	v_add_f32_e32 v66, v163, v66
	v_add_f32_e32 v66, v169, v66
	v_add_f32_e32 v66, v164, v66
	v_add_f32_e32 v66, v166, v66
	v_add_f32_e32 v66, v106, v66
	v_add_f32_e32 v66, v107, v66
	v_add_f32_e32 v66, v108, v66
	v_add_f32_e32 v66, v109, v66
	v_add_f32_e32 v66, v110, v66
	v_add_f32_e32 v66, v111, v66
	v_add_f32_e32 v66, v112, v66
	v_add_f32_e32 v66, v113, v66
	v_add_f32_e32 v66, v120, v66
	v_add_f32_e32 v66, v121, v66
	s_waitcnt lgkmcnt(0)
	v_mfma_f32_32x32x16_bf16 v[70:85], v[102:105], v[130:133], v[70:85]
	v_add_f32_e32 v66, v118, v66
	v_add_f32_e32 v66, v119, v66
	v_add_f32_e32 v66, v116, v66
	v_add_f32_e32 v66, v117, v66
	v_add_f32_e32 v66, v114, v66
	v_add_f32_e32 v239, v115, v66
	v_mov_b32_e32 v240, v239
	s_nop 1
	v_permlane32_swap_b32_e32 v239, v240
	v_cvt_pk_bf16_f32 v66, v176, v179
	v_cvt_pk_bf16_f32 v67, v174, v177
	v_cvt_pk_bf16_f32 v68, v173, v175
	v_cvt_pk_bf16_f32 v69, v171, v172
	v_cvt_pk_bf16_f32 v102, v167, v170
	v_cvt_pk_bf16_f32 v103, v165, v168
	v_cvt_pk_bf16_f32 v104, v163, v169
	v_cvt_pk_bf16_f32 v105, v164, v166
	v_cvt_pk_bf16_f32 v106, v106, v107
	v_cvt_pk_bf16_f32 v107, v108, v109
	v_cvt_pk_bf16_f32 v108, v110, v111
	v_cvt_pk_bf16_f32 v109, v112, v113
	v_cvt_pk_bf16_f32 v110, v120, v121
	v_cvt_pk_bf16_f32 v111, v118, v119
	v_cvt_pk_bf16_f32 v112, v116, v117
	v_cvt_pk_bf16_f32 v113, v114, v115
	s_nop 0
	v_permlane32_swap_b32_e32 v66, v68
	v_permlane32_swap_b32_e32 v67, v69
	v_permlane32_swap_b32_e32 v102, v104
	v_permlane32_swap_b32_e32 v103, v105
	v_permlane32_swap_b32_e32 v106, v108
	v_permlane32_swap_b32_e32 v107, v109
	v_permlane32_swap_b32_e32 v110, v112
	v_permlane32_swap_b32_e32 v111, v113
	v_add_u32_e32 v244, s18, v199
	v_add_u32_e32 v245, s18, v221
	v_add_u32_e32 v114, 1, v244
	v_add_u32_e32 v116, 33, v244
	v_mad_u32_u24 v114, v114, s35, v0
	v_mad_u32_u24 v116, v116, s35, v0
	v_add_u32_e32 v242, 1, v245
	v_lshlrev_b32_e32 v242, 2, v242
	global_load_dwordx4 v[162:165], v114, s[8:9]
	global_load_dwordx4 v[166:169], v116, s[8:9]
	global_load_dwordx4 v[170:173], v114, s[10:11]
	global_load_dwordx4 v[174:177], v116, s[10:11]
	global_load_dword v242, v242, s[4:5]
	ds_read_b64_tr_b16 v[114:115], v227 offset:0
	ds_read_b64_tr_b16 v[116:117], v227 offset:0x800
	ds_read_b64_tr_b16 v[118:119], v227 offset:0x1000
	ds_read_b64_tr_b16 v[120:121], v227 offset:0x1800
	ds_read_b64_tr_b16 v[122:123], v227 offset:0x2000
	ds_read_b64_tr_b16 v[124:125], v227 offset:0x2800
	ds_read_b64_tr_b16 v[126:127], v227 offset:0x3000
	ds_read_b64_tr_b16 v[128:129], v227 offset:0x3800
	s_waitcnt lgkmcnt(0)
; DI void mask_tile(f32x16& p0, f32x16& p1, int dq) {
;     const float NEG = -__builtin_inff();
; #pragma unroll
;     for (int r = 0; r < 16; ++r) {
;         const int c = (r & 3) + 8 * (r >> 2);
;         if ((unsigned)(dq - c) >= WBIG) p0[r] = NEG;
;         if ((unsigned)(dq - c - 32) >= WBIG) p1[r] = NEG;
;     }
; }
; template <int VB>
; DI void pv_tile(f32x16* o, int vb0, bf16x8 pa0, bf16x8 pa1, bf16x8 pa2, bf16x8 pa3) {
;     ...
;     PV_D0(0); PV_D0(1); PV_D0(2); PV_D0(3);
	s_nop 0
	v_mfma_f32_32x32x16_bf16 v[50:65], v[66:69], v[114:117], v[50:65]
	ds_read_b64_tr_b16 v[114:115], v227 offset:0x200
	ds_read_b64_tr_b16 v[116:117], v227 offset:0xa00
	v_mfma_f32_32x32x16_bf16 v[50:65], v[102:105], v[118:121], v[50:65]
	ds_read_b64_tr_b16 v[118:119], v227 offset:0x1200
	ds_read_b64_tr_b16 v[120:121], v227 offset:0x1a00
	v_mfma_f32_32x32x16_bf16 v[50:65], v[106:109], v[122:125], v[50:65]
	ds_read_b64_tr_b16 v[122:123], v227 offset:0x2200
	ds_read_b64_tr_b16 v[124:125], v227 offset:0x2a00
	v_mfma_f32_32x32x16_bf16 v[50:65], v[110:113], v[126:129], v[50:65]
	ds_read_b64_tr_b16 v[126:127], v227 offset:0x3200
	ds_read_b64_tr_b16 v[128:129], v227 offset:0x3a00
	s_waitcnt lgkmcnt(0)
	v_mfma_f32_32x32x16_bf16 v[34:49], v[66:69], v[114:117], v[34:49]
	ds_read_b64_tr_b16 v[114:115], v227 offset:0x400
	ds_read_b64_tr_b16 v[116:117], v227 offset:0xc00
	v_mfma_f32_32x32x16_bf16 v[34:49], v[102:105], v[118:121], v[34:49]
	ds_read_b64_tr_b16 v[118:119], v227 offset:0x1400
	ds_read_b64_tr_b16 v[120:121], v227 offset:0x1c00
	v_mfma_f32_32x32x16_bf16 v[34:49], v[106:109], v[122:125], v[34:49]
	ds_read_b64_tr_b16 v[122:123], v227 offset:0x2400
	ds_read_b64_tr_b16 v[124:125], v227 offset:0x2c00
	v_mfma_f32_32x32x16_bf16 v[34:49], v[110:113], v[126:129], v[34:49]
	ds_read_b64_tr_b16 v[126:127], v227 offset:0x3400
	ds_read_b64_tr_b16 v[128:129], v227 offset:0x3c00
	s_waitcnt lgkmcnt(0)
	v_mfma_f32_32x32x16_bf16 v[18:33], v[66:69], v[114:117], v[18:33]
	ds_read_b64_tr_b16 v[114:115], v227 offset:0x600
	ds_read_b64_tr_b16 v[116:117], v227 offset:0xe00
	v_mfma_f32_32x32x16_bf16 v[18:33], v[102:105], v[118:121], v[18:33]
	ds_read_b64_tr_b16 v[118:119], v227 offset:0x1600
	ds_read_b64_tr_b16 v[120:121], v227 offset:0x1e00
	v_mfma_f32_32x32x16_bf16 v[18:33], v[106:109], v[122:125], v[18:33]
	ds_read_b64_tr_b16 v[122:123], v227 offset:0x2600
	ds_read_b64_tr_b16 v[124:125], v227 offset:0x2e00
	v_mfma_f32_32x32x16_bf16 v[18:33], v[110:113], v[126:129], v[18:33]
	ds_read_b64_tr_b16 v[126:127], v227 offset:0x3600
	ds_read_b64_tr_b16 v[128:129], v227 offset:0x3e00
	s_waitcnt lgkmcnt(0)
	v_mfma_f32_32x32x16_bf16 v[2:17], v[66:69], v[114:117], v[2:17]
	s_cmp_le_i32 s18, s31
	v_mfma_f32_32x32x16_bf16 v[2:17], v[102:105], v[118:121], v[2:17]
	v_mfma_f32_32x32x16_bf16 v[2:17], v[106:109], v[122:125], v[2:17]
	v_mfma_f32_32x32x16_bf16 v[2:17], v[110:113], v[126:129], v[2:17]
	s_cbranch_scc1 .LBB0_538
	v_add_u32_e32 v66, 0x4000007b, v238
	v_cmp_gt_u32_e32 vcc, 2.0, v66
	v_add_u32_e32 v66, 0x5b, v238
	s_nop 0
	v_cndmask_b32_e32 v86, v214, v86, vcc
	v_cmp_lt_u32_e32 vcc, s68, v66
	v_add_u32_e32 v66, 0x7a, v238
	s_nop 0
	v_cndmask_b32_e32 v70, v214, v70, vcc
	v_cmp_lt_u32_e32 vcc, s68, v66
	v_add_u32_e32 v66, 0x5a, v238
	s_nop 0
	v_cndmask_b32_e32 v87, v214, v87, vcc
	v_cmp_lt_u32_e32 vcc, s68, v66
	v_add_u32_e32 v66, 0x79, v238
	s_nop 0
	v_cndmask_b32_e32 v71, v214, v71, vcc
	v_cmp_lt_u32_e32 vcc, s68, v66
	v_add_u32_e32 v66, 0x59, v238
	s_nop 0
	v_cndmask_b32_e32 v88, v214, v88, vcc
	v_cmp_lt_u32_e32 vcc, s68, v66
	v_add_u32_e32 v66, 0x78, v238
	s_nop 0
	v_cndmask_b32_e32 v72, v214, v72, vcc
	v_cmp_lt_u32_e32 vcc, s68, v66
	v_add_u32_e32 v66, 0x58, v238
	s_nop 0
	v_cndmask_b32_e32 v89, v214, v89, vcc
	v_cmp_lt_u32_e32 vcc, s68, v66
	v_add_u32_e32 v66, 0x73, v238
	s_nop 0
	v_cndmask_b32_e32 v73, v214, v73, vcc
	v_cmp_lt_u32_e32 vcc, s68, v66
	v_add_u32_e32 v66, 0x53, v238
	s_nop 0
	v_cndmask_b32_e32 v90, v214, v90, vcc
	v_cmp_lt_u32_e32 vcc, s68, v66
	v_add_u32_e32 v66, 0x72, v238
	s_nop 0
	v_cndmask_b32_e32 v74, v214, v74, vcc
	v_cmp_lt_u32_e32 vcc, s68, v66
	v_add_u32_e32 v66, 0x52, v238
	s_nop 0
	v_cndmask_b32_e32 v91, v214, v91, vcc
	v_cmp_lt_u32_e32 vcc, s68, v66
	v_add_u32_e32 v66, 0x71, v238
	s_nop 0
	v_cndmask_b32_e32 v75, v214, v75, vcc
	v_cmp_lt_u32_e32 vcc, s68, v66
	v_add_u32_e32 v66, 0x51, v238
	s_nop 0
	v_cndmask_b32_e32 v92, v214, v92, vcc
	v_cmp_lt_u32_e32 vcc, s68, v66
	v_add_u32_e32 v66, 0x70, v238
	s_nop 0
	v_cndmask_b32_e32 v76, v214, v76, vcc
	v_cmp_lt_u32_e32 vcc, s68, v66
	v_add_u32_e32 v66, 0x50, v238
	s_nop 0
	v_cndmask_b32_e32 v93, v214, v93, vcc
	v_cmp_lt_u32_e32 vcc, s68, v66
	v_add_u32_e32 v66, 0x6b, v238
	s_nop 0
	v_cndmask_b32_e32 v77, v214, v77, vcc
	v_cmp_lt_u32_e32 vcc, s68, v66
	v_add_u32_e32 v66, 0x4b, v238
	s_nop 0
	v_cndmask_b32_e32 v94, v214, v94, vcc
	v_cmp_lt_u32_e32 vcc, s68, v66
	v_add_u32_e32 v66, 0x6a, v238
	s_nop 0
	v_cndmask_b32_e32 v78, v214, v78, vcc
	v_cmp_lt_u32_e32 vcc, s68, v66
	v_add_u32_e32 v66, 0x4a, v238
	s_nop 0
	v_cndmask_b32_e32 v95, v214, v95, vcc
	v_cmp_lt_u32_e32 vcc, s68, v66
	v_add_u32_e32 v66, 0x69, v238
	s_nop 0
	v_cndmask_b32_e32 v79, v214, v79, vcc
	v_cmp_lt_u32_e32 vcc, s68, v66
	v_add_u32_e32 v66, 0x49, v238
	s_nop 0
	v_cndmask_b32_e32 v96, v214, v96, vcc
	v_cmp_lt_u32_e32 vcc, s68, v66
	v_add_u32_e32 v66, 0x68, v238
	s_nop 0
	v_cndmask_b32_e32 v80, v214, v80, vcc
	v_cmp_lt_u32_e32 vcc, s68, v66
	v_add_u32_e32 v66, 0x48, v238
	s_nop 0
	v_cndmask_b32_e32 v97, v214, v97, vcc
	v_cmp_lt_u32_e32 vcc, s68, v66
	v_add_u32_e32 v66, 0x63, v238
	s_nop 0
	v_cndmask_b32_e32 v81, v214, v81, vcc
	v_cmp_lt_u32_e32 vcc, s68, v66
	v_add_u32_e32 v66, 0x43, v238
	s_nop 0
	v_cndmask_b32_e32 v98, v214, v98, vcc
	v_cmp_lt_u32_e32 vcc, s68, v66
	v_add_u32_e32 v66, 0x62, v238
	s_nop 0
	v_cndmask_b32_e32 v82, v214, v82, vcc
	v_cmp_lt_u32_e32 vcc, s68, v66
	v_add_u32_e32 v66, 0x42, v238
	s_nop 0
	v_cndmask_b32_e32 v99, v214, v99, vcc
	v_cmp_lt_u32_e32 vcc, s68, v66
	v_add_u32_e32 v66, 0x61, v238
	s_nop 0
	v_cndmask_b32_e32 v83, v214, v83, vcc
	v_cmp_lt_u32_e32 vcc, s68, v66
	v_add_u32_e32 v66, 0x41, v238
	s_nop 0
	v_cndmask_b32_e32 v100, v214, v100, vcc
	v_cmp_lt_u32_e32 vcc, s68, v66
	v_add_u32_e32 v66, 0x60, v238
	s_nop 0
	v_cndmask_b32_e32 v84, v214, v84, vcc
	v_cmp_lt_u32_e32 vcc, s68, v66
	v_add_u32_e32 v66, 64, v238
	s_nop 0
	v_cndmask_b32_e32 v101, v214, v101, vcc
	v_cmp_lt_u32_e32 vcc, s68, v66
	s_nop 1
	v_cndmask_b32_e32 v85, v214, v85, vcc

.LBB0_540:
	s_or_b64 exec, exec, s[12:13]
	s_waitcnt lgkmcnt(0)
	s_barrier
	s_add_i32 s12, s19, -1
	s_cmp_lt_i32 s12, s7
	s_cselect_b64 s[0:1], -1, 0
	s_cmp_ge_i32 s12, s7
	s_cbranch_scc1 .Lfa_c2_skip
	v_add_u32_e32 v242, 0x41, v245
	v_add_u32_e32 v194, 0x41, v244
	v_add_u32_e32 v195, 0x61, v244
	v_mad_u32_u24 v194, v194, s35, v0
	v_mad_u32_u24 v195, v195, s35, v0
	v_lshlrev_b32_e32 v242, 2, v242
	global_load_dwordx4 v[162:165], v194, s[8:9]
	global_load_dwordx4 v[166:169], v195, s[8:9]
	global_load_dwordx4 v[170:173], v194, s[10:11]
	global_load_dwordx4 v[174:177], v195, s[10:11]
	global_load_dword v242, v242, s[4:5]

; DI ARef mkref(const PP& p, int L, bool dummy = false) {
;     const int qb = 63 - (L >> 3), hh = L & 7;
;     ARef r;
;     r.Q = p.proj + (size_t)(qb * QB) * LDP + C_FQ + hh * 128; r.O = p.proj + (size_t)(qb * QB) * LDP + C_FQ + hh * 128;
; DI int block(const PP& p, const ARef& cur, volatile int* slot, unsigned* ctr, int base, int total, char* lds, Seam& S, bool dummy, const unsigned* nrm) {
;     ...
;     const int Ln = __builtin_amdgcn_readfirstlane(*slot);
;     ARef nxt = (Ln < total) ? mkref(p, base + Ln, dummy) : cur;
;     ...
;     S.jlo_next = nxt.jlo;
.LBB0_561:
	s_mov_b64 s[0:1], src_shared_base
	s_cmp_lg_u32 s78, -1
	s_cselect_b32 s0, s78, 0
	s_cselect_b32 s1, s1, 0
	s_waitcnt vmcnt(4)
	v_mov_b32_e32 v98, s0
	v_mov_b32_e32 v99, s1
	flat_load_dword v98, v[98:99] sc0 sc1
	s_waitcnt vmcnt(0)
	s_mov_b64 s[14:15], s[2:3]
	s_waitcnt lgkmcnt(0)
	v_readfirstlane_b32 s33, v98
	s_cmpk_lt_i32 s33, 0x300
	s_cselect_b64 s[0:1], -1, 0
	s_cmpk_gt_i32 s33, 0x2ff
	s_cbranch_scc1 .LBB0_563
	s_cmpk_lt_u32 s33, 384
	s_cbranch_scc1 .Lfa_m2_a
	s_cmpk_lt_u32 s33, 640
	s_cbranch_scc1 .Lfa_m2_b
	s_sub_i32 s38, s33, 256
	s_mov_b32 s7, 2
	s_branch .Lfa_m2_md
.Lfa_m2_b:
	s_sub_i32 s39, s33, 384
	s_and_b32 s7, s39, 15
	s_lshr_b32 s39, s39, 4
	s_lshl_b32 s39, s39, 3
	s_addk_i32 s39, 128
	s_lshr_b32 s38, s7, 1
	s_add_i32 s38, s38, s39
	s_and_b32 s7, s7, 1
	s_branch .Lfa_m2_md
.Lfa_m2_a:
	s_mul_i32 s39, s33, 0xaaab
	s_lshr_b32 s39, s39, 20
	s_mul_i32 s7, s39, 24
	s_sub_i32 s7, s33, s7
	s_lshl_b32 s39, s39, 3
	s_cmp_lt_u32 s7, 16
	s_cbranch_scc0 .Lfa_m2_uns
	s_lshr_b32 s38, s7, 1
	s_add_i32 s38, s38, s39
	s_and_b32 s7, s7, 1
	s_branch .Lfa_m2_md
